# grid barrier leaders: dropped the unread per-XCD generation add and the waits for it and for the generation-word add (leaders leave right after the release is visible)
# baseline (speedup 1.0000x reference)
.LBB0_115:
	s_or_b64 exec, exec, s[12:13]
	s_mov_b64 s[12:13], exec
	v_mbcnt_lo_u32_b32 v1, s12, 0
	v_mbcnt_hi_u32_b32 v1, s13, v1
	v_cmp_eq_u32_e32 vcc, 0, v1
	s_nop 0
	s_and_saveexec_b64 s[14:15], vcc
	s_cbranch_execz .LBB0_117
	s_bcnt1_i32_b64 s3, s[12:13]
	v_mov_b32_e32 v1, 0x2000
	v_mov_b32_e32 v2, s3
	s_nop 0
.LBB0_117:
	s_or_b64 exec, exec, s[14:15]
	s_nop 0

.LBB0_197:
	s_or_b64 exec, exec, s[10:11]
	s_mov_b64 s[10:11], exec
	v_mbcnt_lo_u32_b32 v1, s10, 0
	v_mbcnt_hi_u32_b32 v1, s11, v1
	v_cmp_eq_u32_e32 vcc, 0, v1
	s_nop 0
	s_and_saveexec_b64 s[12:13], vcc
	s_cbranch_execz .LBB0_199
	s_bcnt1_i32_b64 s3, s[10:11]
	v_mov_b32_e32 v1, 0x2000
	v_mov_b32_e32 v2, s3
	s_nop 0
.LBB0_199:
	s_or_b64 exec, exec, s[12:13]
	s_nop 0

.LBB0_1416:
	s_or_b64 exec, exec, s[8:9]
	s_mov_b64 s[8:9], exec
	v_mbcnt_lo_u32_b32 v0, s8, 0
	v_mbcnt_hi_u32_b32 v0, s9, v0
	v_cmp_eq_u32_e32 vcc, 0, v0
	s_nop 0
	s_and_saveexec_b64 s[12:13], vcc
	s_cbranch_execz .LBB0_1418
	s_bcnt1_i32_b64 s3, s[8:9]
	v_mov_b32_e32 v0, 0x2000
	v_mov_b32_e32 v1, s3
	s_nop 0
